# ph_win last half-round after the grid sync (guarded for 256 workgroups) with ret_kv rebalanced; dil_attn and ph_down reversed traversal
# speedup vs baseline: 1.0099x; 1.0024x over previous
; DI int opaque_bid() { int t = blockIdx.x; asm volatile("" : "+s"(t)); return t; }
;     DI bool next(int i, Unit& u) const {
;         const long L = (long)i * G + c; if (L >= nwg) return false;
; DI void ph_win(LAS unsigned char* lds, int l, int g) {
;     ...
;     pg8::Gemm gm{(const bf16_t*)(ws + WS_XB) + rb * D, (const bf16_t*)(ws + WS_W + (size_t)l * LW + OW_IN), GT, INW, D}; pg8::StaticOrder S; S.init(GT, INW, gridDim.x, opaque_bid());
;     pg8::EpiZ E{(bf16_t*)(ws + WS_Z), (const float*)(ws + WS_SLOT) + rb * 16, (const float*)(ws + WS_ROPE), (const float*)(ws + WS_ROPE) + SEQ * 64}; pg8::gemm_phase(lds, gm, S, E);
.LBB0_81:
	s_mov_b32 s98, 0
	s_movk_i32 s99, 0x900
	s_mov_b32 s100, 0
	s_cmp_eq_u32 s14, 0x100
	s_cbranch_scc1 .Lwin_again
	s_mov_b32 s98, 2
	s_movk_i32 s99, 0x980

; DI void ret_kv_phase(int l, unsigned char* lds_g, LAS unsigned char* lds) {
;     const int tid = opaque_tid(), lane = tid & 63, w = tid >> 6, fr = lane & 15, fq = lane >> 4;
;     const unsigned lbase = (unsigned)(size_t)lds_g;
;     const bf16_t* Z = (const bf16_t*)(arg_ws() + WS_Z); bf16_t* KV = (bf16_t*)(arg_ws() + WS_KV);
;     constexpr int OV = 0, OKF = 128 * RV_PITCH, OKB = OKF + 128 * RK_PITCH;
;     for (int item = opaque_bid(); item < GB * 4 * 32; item += gridDim.x) {
;         const int n = item & 31, h = (item >> 5) & 3, bl = item >> 7;
;         const size_t row0 = (size_t)bl * SEQ + n * 128;
;         const float de_f = arg_in(I_DEC)[(l * 2 + 0) * 4 + h], de_b = arg_in(I_DEC)[(l * 2 + 1) * 4 + h];
;         const float l2f = log1pf(-exp2f(-de_f)) * 1.44269504f, l2b = log1pf(-exp2f(-de_b)) * 1.44269504f;
; #pragma unroll
;         for (int i = 0; i < 8; ++i) { const int id = tid + 512 * i, r = id >> 5, ch = id & 31;
;             const u32x4 v = *(const u32x4*)(Z + (row0 + r) * INW + ZC_RV + h * 256 + ch * 8);
;             *(LAS u32x4*)(lds + OV + r * RV_PITCH + ch * 16) = v; }
; #pragma unroll
;         for (int i = 0; i < 4; ++i) { const int id = tid + 512 * i, r = id >> 4, ch = id & 15;
;             const u32x4 v = *(const u32x4*)(Z + (row0 + r) * INW + ZC_RK + h * 128 + ch * 8);
;             const float sf = fexp2(l2f * (float)(127 - r)), sb = fexp2(l2b * (float)r);
;             u32x4 f, b;
;             f.x = pk2(bflo(v.x) * sf, bfhi(v.x) * sf); f.y = pk2(bflo(v.y) * sf, bfhi(v.y) * sf); f.z = pk2(bflo(v.z) * sf, bfhi(v.z) * sf); f.w = pk2(bflo(v.w) * sf, bfhi(v.w) * sf);
;             b.x = pk2(bflo(v.x) * sb, bfhi(v.x) * sb); b.y = pk2(bflo(v.y) * sb, bfhi(v.y) * sb); b.z = pk2(bflo(v.z) * sb, bfhi(v.z) * sb); b.w = pk2(bflo(v.w) * sb, bfhi(v.w) * sb);
;             *(LAS u32x4*)(lds + OKF + r * RK_PITCH + ch * 16) = f; *(LAS u32x4*)(lds + OKB + r * RK_PITCH + ch * 16) = b; }
;         __syncthreads();
;         f32x4 acc[2][8][2];
; #pragma unroll
;         for (int d = 0; d < 2; ++d)
; #pragma unroll
;             for (int mt = 0; mt < 8; ++mt)
; #pragma unroll
;                 for (int nt = 0; nt < 2; ++nt) acc[d][mt][nt] = (f32x4){0.f, 0.f, 0.f, 0.f};
;         const int q = fr >> 2, p = fr & 3;
; #pragma unroll 1
;         for (int ks = 0; ks < 4; ++ks) {
;             const int tr0 = 32 * ks + 8 * fq + q;
.LBB0_189:
	s_or_b64 exec, exec, s[4:5]
	s_cmp_lg_u32 s98, 0
	s_cbranch_scc1 .Lwin_done
	s_mov_b32 s98, 1
	s_movk_i32 s99, 0x980
	s_movk_i32 s100, 0x900
	s_branch .Lwin_again
.Lwin_done:
	v_mov_b32_e32 v2, v242
	s_mov_b64 s[8:9], s[0:1]
	s_mov_b64 s[6:7], s[0:1]
	s_mov_b32 s4, s2
	s_movk_i32 s101, 0x1ff
	s_mov_b32 s100, s14
	s_cmp_lg_u32 s98, 1
	s_cbranch_scc1 .Lkv_generic
	s_movk_i32 s100, 0x80
	s_cmp_lt_u32 s2, 0x80
	s_cselect_b32 s101, 0x7f, s101
.Lkv_generic:
	s_waitcnt lgkmcnt(0)
	s_barrier
	s_cmpk_gt_i32 s4, 0x1ff
	s_cbranch_scc1 .LBB0_194
	v_and_b32_e32 v3, 15, v2
	v_and_b32_e32 v1, 31, v2
	v_lshlrev_b32_e32 v8, 4, v3
	v_readlane_b32 s5, v255, 3
	s_waitcnt vmcnt(8)
	v_lshlrev_b32_e32 v4, 3, v1
	v_lshl_add_u32 v7, v1, 4, 0
	v_add_u32_e32 v1, s5, v8
	v_add_u32_e32 v160, s82, v8
	v_lshlrev_b32_e32 v8, 3, v2
	v_and_b32_e32 v14, 24, v8
	v_ashrrev_i32_e32 v8, 1, v2
	v_and_b32_e32 v8, 0xffffffe0, v8
	s_load_dwordx2 s[8:9], s[8:9], 0xa8
	s_nop 0
	s_load_dwordx2 s[22:23], s[6:7], 0xa8
	v_lshlrev_b32_e32 v6, 3, v3
	v_ashrrev_i32_e32 v9, 31, v8
	v_or_b32_e32 v8, v8, v3
	v_add_u32_e32 v3, 0x200, v2
	v_ashrrev_i32_e32 v146, 4, v2
	v_bfe_u32 v5, v2, 4, 2
	v_bfe_u32 v12, v2, 2, 2
	v_and_b32_e32 v13, 0xffffffc0, v2
	v_ashrrev_i32_e32 v130, 5, v2
	v_add_u32_e32 v17, 0x400, v2
	v_add_u32_e32 v19, 0x600, v2
	v_add_u32_e32 v21, 0x800, v2
	v_add_u32_e32 v22, 0xa00, v2
	v_add_u32_e32 v23, 0xc00, v2
	v_add_u32_e32 v24, 0xe00, v2
	v_sub_u32_e32 v2, 0x7f, v146
	v_ashrrev_i32_e32 v148, 4, v3
	v_cvt_f32_i32_e32 v161, v2
	v_sub_u32_e32 v2, 0x7f, v148
	v_ashrrev_i32_e32 v150, 4, v17
	v_cvt_f32_i32_e32 v164, v2
	v_sub_u32_e32 v2, 0x7f, v150
	v_ashrrev_i32_e32 v152, 4, v19
	v_lshlrev_b32_e32 v10, 3, v5
	v_mov_b32_e32 v11, v0
	v_cvt_f32_i32_e32 v167, v2
	v_sub_u32_e32 v2, 0x7f, v152
	s_waitcnt lgkmcnt(0)
	s_add_u32 s6, s8, 0x16c00000
	v_lshl_add_u64 v[10:11], s[22:23], 0, v[10:11]
	v_ashrrev_i32_e32 v132, 5, v3
	v_cvt_f32_i32_e32 v170, v2
	v_lshlrev_b64 v[2:3], 8, v[8:9]
	s_addc_u32 s7, s9, 0
	v_lshl_add_u64 v[2:3], v[10:11], 0, v[2:3]
	s_mov_b64 s[8:9], 0x29c00000
	v_cvt_f32_i32_e32 v162, v146
	v_cvt_f32_i32_e32 v165, v148
	v_cvt_f32_i32_e32 v168, v150
	v_cvt_f32_i32_e32 v171, v152
	v_lshl_add_u64 v[154:155], v[2:3], 0, s[8:9]
	v_mul_u32_u24_e32 v2, 0x880, v5
	v_mul_u32_u24_e32 v3, 0x110, v12
	v_ashrrev_i32_e32 v134, 5, v17
	v_ashrrev_i32_e32 v136, 5, v19
	v_ashrrev_i32_e32 v138, 5, v21
	v_ashrrev_i32_e32 v140, 5, v22
	v_ashrrev_i32_e32 v142, 5, v23
	v_ashrrev_i32_e32 v144, 5, v24
	v_add3_u32 v173, v2, v3, v14
	v_mul_u32_u24_e32 v2, 0x210, v12
	s_movk_i32 s5, 0x1080
	v_mul_lo_u32 v15, v130, s83
	v_mul_lo_u32 v16, v132, s83
	v_mul_lo_u32 v18, v134, s83
	v_mul_lo_u32 v20, v136, s83
	v_mul_lo_u32 v21, v138, s83
	v_mul_lo_u32 v22, v140, s83
	v_mul_lo_u32 v23, v142, s83
	v_mul_lo_u32 v24, v144, s83
	v_mad_u32_u24 v2, v5, s5, v2
	v_ashrrev_i32_e32 v131, 31, v130
	v_ashrrev_i32_e32 v133, 31, v132
	v_ashrrev_i32_e32 v135, 31, v134
	v_ashrrev_i32_e32 v137, 31, v136
	v_ashrrev_i32_e32 v139, 31, v138
	v_ashrrev_i32_e32 v141, 31, v140
	v_ashrrev_i32_e32 v143, 31, v142
	v_ashrrev_i32_e32 v145, 31, v144
	v_ashrrev_i32_e32 v147, 31, v146
	v_mul_lo_u32 v163, v146, s84
	v_ashrrev_i32_e32 v149, 31, v148
	v_mul_lo_u32 v166, v148, s84
	v_ashrrev_i32_e32 v151, 31, v150
	v_mul_lo_u32 v169, v150, s84
	v_ashrrev_i32_e32 v153, 31, v152
	v_mul_lo_u32 v172, v152, s84
	v_add3_u32 v174, v2, v13, v14
	v_lshlrev_b32_e32 v156, 1, v4
	v_add_u32_e32 v175, v7, v15
	v_add_u32_e32 v176, v7, v16
	v_add_u32_e32 v177, v7, v18
	v_add_u32_e32 v178, v7, v20
	v_add_u32_e32 v179, v7, v21
	v_add_u32_e32 v180, v7, v22
	v_add_u32_e32 v181, v7, v23
	v_add_u32_e32 v182, v7, v24
	v_lshlrev_b32_e32 v158, 1, v6

; DI f32x4 mfma16(bf16x8 a, bf16x8 b, f32x4 c) { return __builtin_amdgcn_mfma_f32_16x16x32_bf16(a, b, c, 0, 0, 0); }
; DI void ret_kv_phase(int l, unsigned char* lds_g, LAS unsigned char* lds) {
;     ...
;         const int q = fr >> 2, p = fr & 3;
; #pragma unroll 1
;         for (int ks = 0; ks < 4; ++ks) {
;             const int tr0 = 32 * ks + 8 * fq + q;
;             bf16x8 Bv[2];
; #pragma unroll
;             for (int nt = 0; nt < 2; ++nt) { const unsigned ad = lbase + OV + tr0 * RV_PITCH + (32 * w + 16 * nt + 4 * p) * 2; Bv[nt] = tr_frag(ad, ad + 4 * RV_PITCH); }
; #pragma unroll
;             for (int d = 0; d < 2; ++d) { const unsigned ad = lbase + (d ? OKB : OKF) + tr0 * RK_PITCH + (4 * p) * 2; bf16x8 Ak[8]; tr8(ad, ad + 4 * RK_PITCH, Ak);
; #pragma unroll
;                 for (int mt = 0; mt < 8; ++mt)
; #pragma unroll
;                     for (int nt = 0; nt < 2; ++nt) acc[d][mt][nt] = mfma16(Ak[mt], Bv[nt], acc[d][mt][nt]); }
;         }
.LBB0_192:
	s_cmp_lg_u32 0, -1
	s_cselect_b32 s8, 0, 0
	v_add_u32_e32 v183, s8, v157
	v_add_u32_e32 v188, 0x840, v183
	ds_read_b64_tr_b16 v[184:185], v183
	ds_read_b64_tr_b16 v[186:187], v188
	s_waitcnt lgkmcnt(0)
	v_add_u32_e32 v192, s8, v159
	v_add_u32_e32 v193, 32, v183
	v_add_u32_e32 v195, 0x860, v183
	ds_read_b64_tr_b16 v[188:189], v193
	ds_read_b64_tr_b16 v[190:191], v195
	s_waitcnt lgkmcnt(0)
	v_add_u32_e32 v204, 0x10800, v192
	v_add_u32_e32 v205, 0x10c40, v192
	ds_read_b64_tr_b16 v[214:215], v204
	ds_read_b64_tr_b16 v[216:217], v205
	ds_read_b64_tr_b16 v[210:211], v204 offset:32
	ds_read_b64_tr_b16 v[212:213], v205 offset:32
	ds_read_b64_tr_b16 v[206:207], v204 offset:64
	ds_read_b64_tr_b16 v[208:209], v205 offset:64
	ds_read_b64_tr_b16 v[200:201], v204 offset:96
	ds_read_b64_tr_b16 v[202:203], v205 offset:96
	s_waitcnt lgkmcnt(0)
	v_add_u32_e32 v183, 0x10880, v192
	v_mfma_f32_16x16x32_bf16 v[126:129], v[214:217], v[184:187], v[126:129]
	v_add_u32_e32 v193, 0x10cc0, v192
	s_add_i32 s5, s5, -1
	v_add_u32_e32 v159, 0x2200, v159
	v_mfma_f32_16x16x32_bf16 v[106:109], v[214:217], v[188:191], v[106:109]
	s_cmp_eq_u32 s5, 0
	v_add_u32_e32 v157, 0x4200, v157
	v_mfma_f32_16x16x32_bf16 v[122:125], v[210:213], v[184:187], v[122:125]
	v_mfma_f32_16x16x32_bf16 v[98:101], v[210:213], v[188:191], v[98:101]
	v_mfma_f32_16x16x32_bf16 v[118:121], v[206:209], v[184:187], v[118:121]
	v_mfma_f32_16x16x32_bf16 v[90:93], v[206:209], v[188:191], v[90:93]
	v_mfma_f32_16x16x32_bf16 v[114:117], v[200:203], v[184:187], v[114:117]
	v_mfma_f32_16x16x32_bf16 v[82:85], v[200:203], v[188:191], v[82:85]
	ds_read_b64_tr_b16 v[214:215], v183
	ds_read_b64_tr_b16 v[216:217], v193
	ds_read_b64_tr_b16 v[210:211], v183 offset:32
	ds_read_b64_tr_b16 v[212:213], v193 offset:32
	ds_read_b64_tr_b16 v[206:207], v183 offset:64
	ds_read_b64_tr_b16 v[208:209], v193 offset:64
	ds_read_b64_tr_b16 v[200:201], v183 offset:96
	ds_read_b64_tr_b16 v[202:203], v193 offset:96
	s_waitcnt lgkmcnt(0)
	v_add_u32_e32 v183, 0x19000, v192
	v_add_u32_e32 v193, 0x19440, v192
	v_mfma_f32_16x16x32_bf16 v[110:113], v[214:217], v[184:187], v[110:113]
	v_mfma_f32_16x16x32_bf16 v[78:81], v[214:217], v[188:191], v[78:81]
	v_mfma_f32_16x16x32_bf16 v[102:105], v[210:213], v[184:187], v[102:105]
	v_mfma_f32_16x16x32_bf16 v[74:77], v[210:213], v[188:191], v[74:77]
	v_mfma_f32_16x16x32_bf16 v[94:97], v[206:209], v[184:187], v[94:97]
	v_mfma_f32_16x16x32_bf16 v[70:73], v[206:209], v[188:191], v[70:73]
	v_mfma_f32_16x16x32_bf16 v[86:89], v[200:203], v[184:187], v[86:89]
	v_mfma_f32_16x16x32_bf16 v[66:69], v[200:203], v[188:191], v[66:69]
	ds_read_b64_tr_b16 v[214:215], v183
	ds_read_b64_tr_b16 v[216:217], v193
	ds_read_b64_tr_b16 v[210:211], v183 offset:32
	ds_read_b64_tr_b16 v[212:213], v193 offset:32
	ds_read_b64_tr_b16 v[206:207], v183 offset:64
	ds_read_b64_tr_b16 v[208:209], v193 offset:64
	ds_read_b64_tr_b16 v[200:201], v183 offset:96
	ds_read_b64_tr_b16 v[202:203], v193 offset:96
	s_waitcnt lgkmcnt(0)
	v_add_u32_e32 v183, 0x19080, v192
	v_add_u32_e32 v192, 0x194c0, v192
	v_mfma_f32_16x16x32_bf16 v[62:65], v[214:217], v[184:187], v[62:65]
	v_mfma_f32_16x16x32_bf16 v[34:37], v[214:217], v[188:191], v[34:37]
	v_mfma_f32_16x16x32_bf16 v[54:57], v[210:213], v[184:187], v[54:57]
	v_mfma_f32_16x16x32_bf16 v[26:29], v[210:213], v[188:191], v[26:29]
	v_mfma_f32_16x16x32_bf16 v[50:53], v[206:209], v[184:187], v[50:53]
	v_mfma_f32_16x16x32_bf16 v[18:21], v[206:209], v[188:191], v[18:21]
	v_mfma_f32_16x16x32_bf16 v[46:49], v[200:203], v[184:187], v[46:49]
	v_mfma_f32_16x16x32_bf16 v[14:17], v[200:203], v[188:191], v[14:17]
	ds_read_b64_tr_b16 v[214:215], v183
	ds_read_b64_tr_b16 v[216:217], v192
	ds_read_b64_tr_b16 v[210:211], v183 offset:32
	ds_read_b64_tr_b16 v[212:213], v192 offset:32
	ds_read_b64_tr_b16 v[206:207], v183 offset:64
	ds_read_b64_tr_b16 v[208:209], v192 offset:64
	ds_read_b64_tr_b16 v[200:201], v183 offset:96
	ds_read_b64_tr_b16 v[202:203], v192 offset:96
	s_waitcnt lgkmcnt(0)
	s_nop 0
	v_mfma_f32_16x16x32_bf16 v[38:41], v[214:217], v[184:187], v[38:41]
	v_mfma_f32_16x16x32_bf16 v[10:13], v[214:217], v[188:191], v[10:13]
	v_mfma_f32_16x16x32_bf16 v[30:33], v[210:213], v[184:187], v[30:33]
	v_mfma_f32_16x16x32_bf16 v[6:9], v[210:213], v[188:191], v[6:9]
	v_mfma_f32_16x16x32_bf16 v[22:25], v[206:209], v[184:187], v[22:25]
	v_mfma_f32_16x16x32_bf16 v[2:5], v[206:209], v[188:191], v[2:5]
	v_mfma_f32_16x16x32_bf16 v[58:61], v[200:203], v[184:187], v[58:61]
	v_mfma_f32_16x16x32_bf16 v[42:45], v[200:203], v[188:191], v[42:45]
	s_cbranch_scc0 .LBB0_192
; DI int opaque_bid() { int t = blockIdx.x; asm volatile("" : "+s"(t)); return t; }
; DI unsigned pk2(float lo, float hi) { unsigned r; asm("v_cvt_pk_bf16_f32 %0, %1, %2" : "=v"(r) : "v"(lo), "v"(hi)); return r; }
; DI void ret_kv_phase(int l, unsigned char* lds_g, LAS unsigned char* lds) {
;     ...
;     for (int item = opaque_bid(); item < GB * 4 * 32; item += gridDim.x) {
;     ...
; #pragma unroll
;         for (int d = 0; d < 2; ++d)
; #pragma unroll
;             for (int nt = 0; nt < 2; ++nt)
; #pragma unroll
;                 for (int mt = 0; mt < 8; ++mt)
;                     { u32x2 o; o.x = pk2(acc[d][mt][nt][0], acc[d][mt][nt][1]); o.y = pk2(acc[d][mt][nt][2], acc[d][mt][nt][3]);
;                       *(u32x2*)(KV + (((size_t)item * 2 + d) * 256 + 32 * w + 16 * nt + fr) * 128 + 16 * mt + 4 * fq) = o; }
;         __syncthreads();
	s_ashr_i32 s5, s4, 31
	s_lshl_b64 s[8:9], s[4:5], 17
	v_lshl_add_u64 v[184:185], v[154:155], 0, s[8:9]
	v_cvt_pk_bf16_f32 v86, v86, v87
	v_cvt_pk_bf16_f32 v87, v88, v89
	v_add_co_u32_e32 v88, vcc, s77, v184
	s_mov_b32 s5, 0x10000
	s_nop 0
	v_addc_co_u32_e32 v89, vcc, 0, v185, vcc
	v_cvt_pk_bf16_f32 v62, v62, v63
	v_cvt_pk_bf16_f32 v63, v64, v65
	v_add_co_u32_e32 v64, vcc, s5, v184
	v_cvt_pk_bf16_f32 v66, v66, v67
	s_mov_b32 s5, 0x11000
	s_nop 0
	v_addc_co_u32_e32 v65, vcc, 0, v185, vcc
	v_cvt_pk_bf16_f32 v22, v22, v23
	v_cvt_pk_bf16_f32 v23, v24, v25
	global_store_dwordx2 v[184:185], v[86:87], off offset:224
	v_cvt_pk_bf16_f32 v86, v106, v107
	v_cvt_pk_bf16_f32 v87, v108, v109
	v_cvt_pk_bf16_f32 v67, v68, v69
	global_store_dwordx2 v[88:89], v[66:67], off offset:224
	v_add_co_u32_e32 v66, vcc, s5, v184
	global_store_dwordx2 v[64:65], v[22:23], off offset:192
	v_cvt_pk_bf16_f32 v22, v58, v59
	v_cvt_pk_bf16_f32 v23, v60, v61
	s_add_i32 s4, s4, s100
	global_store_dwordx2 v[88:89], v[86:87], off
	v_cvt_pk_bf16_f32 v86, v98, v99
	v_cvt_pk_bf16_f32 v87, v100, v101
	v_addc_co_u32_e32 v67, vcc, 0, v185, vcc
	global_store_dwordx2 v[64:65], v[22:23], off offset:224
	v_cvt_pk_bf16_f32 v22, v34, v35
	v_cvt_pk_bf16_f32 v23, v36, v37
	v_cvt_pk_bf16_f32 v2, v2, v3
	v_cvt_pk_bf16_f32 v3, v4, v5
	s_cmp_gt_i32 s4, s101
	v_cvt_pk_bf16_f32 v126, v126, v127
	v_cvt_pk_bf16_f32 v127, v128, v129
	global_store_dwordx2 v[184:185], v[126:127], off
	v_cvt_pk_bf16_f32 v122, v122, v123
	v_cvt_pk_bf16_f32 v123, v124, v125
	global_store_dwordx2 v[184:185], v[122:123], off offset:32
	v_cvt_pk_bf16_f32 v118, v118, v119
	v_cvt_pk_bf16_f32 v119, v120, v121
	global_store_dwordx2 v[184:185], v[118:119], off offset:64
	v_cvt_pk_bf16_f32 v114, v114, v115
	v_cvt_pk_bf16_f32 v115, v116, v117
	global_store_dwordx2 v[184:185], v[114:115], off offset:96
	v_cvt_pk_bf16_f32 v110, v110, v111
	v_cvt_pk_bf16_f32 v111, v112, v113
	global_store_dwordx2 v[184:185], v[110:111], off offset:128
	v_cvt_pk_bf16_f32 v102, v102, v103
	v_cvt_pk_bf16_f32 v103, v104, v105
	global_store_dwordx2 v[184:185], v[102:103], off offset:160
	v_cvt_pk_bf16_f32 v94, v94, v95
	v_cvt_pk_bf16_f32 v95, v96, v97
	global_store_dwordx2 v[184:185], v[94:95], off offset:192
	global_store_dwordx2 v[88:89], v[86:87], off offset:32
	v_cvt_pk_bf16_f32 v86, v90, v91
	v_cvt_pk_bf16_f32 v87, v92, v93
	global_store_dwordx2 v[88:89], v[86:87], off offset:64
	v_cvt_pk_bf16_f32 v82, v82, v83
	v_cvt_pk_bf16_f32 v83, v84, v85
	global_store_dwordx2 v[88:89], v[82:83], off offset:96
	v_cvt_pk_bf16_f32 v78, v78, v79
	v_cvt_pk_bf16_f32 v79, v80, v81
	global_store_dwordx2 v[88:89], v[78:79], off offset:128
	v_cvt_pk_bf16_f32 v74, v74, v75
	v_cvt_pk_bf16_f32 v75, v76, v77
	global_store_dwordx2 v[88:89], v[74:75], off offset:160
	v_cvt_pk_bf16_f32 v70, v70, v71
	v_cvt_pk_bf16_f32 v71, v72, v73
	global_store_dwordx2 v[88:89], v[70:71], off offset:192
	global_store_dwordx2 v[66:67], v[62:63], off offset:-4096
	v_cvt_pk_bf16_f32 v54, v54, v55
	v_cvt_pk_bf16_f32 v55, v56, v57
	global_store_dwordx2 v[64:65], v[54:55], off offset:32
	v_cvt_pk_bf16_f32 v50, v50, v51
	v_cvt_pk_bf16_f32 v51, v52, v53
	global_store_dwordx2 v[64:65], v[50:51], off offset:64
	v_cvt_pk_bf16_f32 v46, v46, v47
	v_cvt_pk_bf16_f32 v47, v48, v49
	global_store_dwordx2 v[64:65], v[46:47], off offset:96
	v_cvt_pk_bf16_f32 v38, v38, v39
	v_cvt_pk_bf16_f32 v39, v40, v41
	global_store_dwordx2 v[64:65], v[38:39], off offset:128
	v_cvt_pk_bf16_f32 v30, v30, v31
	v_cvt_pk_bf16_f32 v31, v32, v33
	global_store_dwordx2 v[64:65], v[30:31], off offset:160
	global_store_dwordx2 v[66:67], v[22:23], off
	v_cvt_pk_bf16_f32 v22, v26, v27
	v_cvt_pk_bf16_f32 v23, v28, v29
	global_store_dwordx2 v[66:67], v[22:23], off offset:32
	v_cvt_pk_bf16_f32 v18, v18, v19
	v_cvt_pk_bf16_f32 v19, v20, v21
	global_store_dwordx2 v[66:67], v[18:19], off offset:64
	v_cvt_pk_bf16_f32 v14, v14, v15
	v_cvt_pk_bf16_f32 v15, v16, v17
	global_store_dwordx2 v[66:67], v[14:15], off offset:96
	v_cvt_pk_bf16_f32 v10, v10, v11
	v_cvt_pk_bf16_f32 v11, v12, v13
	global_store_dwordx2 v[66:67], v[10:11], off offset:128
	v_cvt_pk_bf16_f32 v6, v6, v7
	v_cvt_pk_bf16_f32 v7, v8, v9
	global_store_dwordx2 v[66:67], v[6:7], off offset:160
	global_store_dwordx2 v[66:67], v[2:3], off offset:192
	v_cvt_pk_bf16_f32 v2, v42, v43
	v_cvt_pk_bf16_f32 v3, v44, v45
	global_store_dwordx2 v[66:67], v[2:3], off offset:224
	s_barrier
	s_cbranch_scc0 .LBB0_191
